# attention work-queue class split thresholds 43,35,31,31 (rebalanced after the loop got faster)
# speedup vs baseline: 1.0114x; 1.0114x over previous
.Lqa_prompt:
	s_add_i32 s63, s26, -4
	s_and_b32 s64, s62, 1
	s_lshr_b32 s65, s62, 1
	s_mov_b32 s67, 0
	s_movk_i32 s66, 43
	s_sub_i32 s59, 64, s66
	s_cmp_eq_u32 s64, 0
	s_cselect_b32 s59, s59, s66
	s_cmp_lt_u32 s63, s59
	s_cbranch_scc1 .Lqa_found
	s_sub_i32 s63, s63, s59
	s_addk_i32 s67, 0x100
	s_movk_i32 s66, 35
	s_sub_i32 s59, 64, s66
	s_cmp_eq_u32 s64, 0
	s_cselect_b32 s59, s59, s66
	s_cmp_lt_u32 s63, s59
	s_cbranch_scc1 .Lqa_found
	s_sub_i32 s63, s63, s59
	s_addk_i32 s67, 0x100
	s_movk_i32 s66, 31
	s_sub_i32 s59, 64, s66
	s_cmp_eq_u32 s64, 0
	s_cselect_b32 s59, s59, s66
	s_cmp_lt_u32 s63, s59
	s_cbranch_scc1 .Lqa_found
	s_sub_i32 s63, s63, s59
	s_addk_i32 s67, 0x100
	s_movk_i32 s66, 31
	s_sub_i32 s59, 64, s66
	s_cmp_eq_u32 s64, 0
	s_cselect_b32 s59, s59, s66
	s_cmp_lt_u32 s63, s59
	s_cbranch_scc1 .Lqa_found
	s_sub_i32 s63, s63, s59
	s_addk_i32 s67, 0x100
	s_cmp_lt_u32 s63, 0x41
	s_cbranch_scc1 .Lqa_lru
	s_sub_i32 s63, s63, 0x41
	s_add_i32 s98, s98, 1
	s_cmp_ge_u32 s98, 8
	s_cbranch_scc1 .LBB0_1418
	s_add_i32 s62, s80, s98
	s_and_b32 s62, s62, 7
	s_lshl_b32 s63, s62, 6
	s_add_u32 s8, s86, 0x1e28f900
	s_addc_u32 s9, s87, 0
	s_add_u32 s8, s8, s63
	s_addc_u32 s9, s9, 0
	s_barrier
	s_and_saveexec_b64 s[0:1], s[82:83]
	s_cbranch_execz .Lqa_nodraw
	v_mov_b32_e32 v2, 0
	v_mov_b32_e32 v3, 1
	s_nop 1
	global_atomic_add v3, v2, v3, s[8:9] sc0
	s_waitcnt vmcnt(0)
	v_mov_b32_e32 v2, s3
	ds_write_b32 v2, v3
